# attention QK: first MFMA pair issued after two fragment stages; third-stage reads and tile DMA issued under the first MFMAs
# speedup vs baseline: 1.0099x; 1.0022x over previous
; #define LAS __attribute__((address_space(3)))
; __device__ __forceinline__ void attn_issue_v(const Frame& F, const unsigned char* vtile, LAS unsigned char* buf) {
;     unsigned lo = F.lane * 16; asm volatile("" : "+v"(lo));
; #pragma unroll
;     for (int j = 0; j < 2; ++j) __builtin_amdgcn_global_load_lds((const unsigned*)(vtile + (size_t)(F.wave * 2 + j) * 1024 + lo), (LAS unsigned*)(buf + (F.wave * 2 + j) * 1024), 16, 0, 0);
; }
.LBB0_1013:
	s_lshl_b32 s89, s89, 14
	s_add_u32 s92, s42, s89
	s_addc_u32 s93, s43, 0
	s_lshl_b32 s89, s75, 14
	s_waitcnt vmcnt(8)
	s_add_i32 s89, s89, 0
	v_mov_b32_e32 v2, v164
	s_waitcnt lgkmcnt(0)
	s_barrier
	s_setprio 1
	s_add_i32 s89, s89, 0x12000
	s_add_i32 vcc_lo, s89, s59
	s_add_i32 vcc_hi, s89, s60
	s_add_u32 s98, s92, s14
	s_addc_u32 s99, s93, s15
	s_add_u32 s100, s92, s16
	s_addc_u32 s101, s93, s17
	s_cmp_gt_i32 s90, s70
	s_cbranch_scc1 .Lmy_attn_skipqk_b
	s_mul_i32 s89, s0, 0x6000
	v_add_u32_e32 v2, s89, v174
	v_add_u32_e32 v16, s89, v175
	ds_read_b128 v[4:7], v2
	ds_read_b128 v[8:11], v2 offset:12288
	ds_read_b128 v[12:15], v16
	ds_read_b128 v[186:189], v16 offset:12288
	v_add_u32_e32 v17, s89, v176
	v_add_u32_e32 v185, s89, v177
	ds_read_b128 v[190:193], v17
	ds_read_b128 v[194:197], v17 offset:12288
	ds_read_b128 v[198:201], v185
	ds_read_b128 v[202:205], v185 offset:12288
	s_waitcnt lgkmcnt(5)
	v_mfma_f32_32x32x16_bf16 v[98:113], v[4:7], v[114:117], 0
	v_mfma_f32_32x32x16_bf16 v[98:113], v[12:15], v[118:121], v[98:113]
	ds_read_b128 v[206:209], v2 offset:128
	ds_read_b128 v[210:213], v2 offset:12416
	ds_read_b128 v[214:217], v16 offset:128
	ds_read_b128 v[218:221], v16 offset:12416
	s_waitcnt lgkmcnt(8)
	v_mfma_f32_32x32x16_bf16 v[82:97], v[8:11], v[114:117], 0
	s_mov_b32 m0, vcc_lo
	s_nop 0
	global_load_lds_dwordx4 v164, s[98:99]
	v_mfma_f32_32x32x16_bf16 v[82:97], v[186:189], v[118:121], v[82:97]
	s_mov_b32 m0, vcc_hi
	s_nop 0
	global_load_lds_dwordx4 v164, s[100:101]
	ds_read_b128 v[4:7], v17 offset:128
	ds_read_b128 v[8:11], v17 offset:12416
	ds_read_b128 v[12:15], v185 offset:128
	ds_read_b128 v[186:189], v185 offset:12416
	s_waitcnt lgkmcnt(8)
	v_mfma_f32_32x32x16_bf16 v[98:113], v[190:193], v[122:125], v[98:113]
	v_mfma_f32_32x32x16_bf16 v[98:113], v[198:201], v[126:129], v[98:113]
	v_mfma_f32_32x32x16_bf16 v[82:97], v[194:197], v[122:125], v[82:97]
	v_mfma_f32_32x32x16_bf16 v[82:97], v[202:205], v[126:129], v[82:97]
	ds_read_b128 v[190:193], v2 offset:256
	ds_read_b128 v[194:197], v2 offset:12544
	ds_read_b128 v[198:201], v16 offset:256
	ds_read_b128 v[202:205], v16 offset:12544
	s_waitcnt lgkmcnt(8)
	v_mfma_f32_32x32x16_bf16 v[98:113], v[206:209], v[130:133], v[98:113]
	v_mfma_f32_32x32x16_bf16 v[98:113], v[214:217], v[134:137], v[98:113]
	v_mfma_f32_32x32x16_bf16 v[82:97], v[210:213], v[130:133], v[82:97]
	v_mfma_f32_32x32x16_bf16 v[82:97], v[218:221], v[134:137], v[82:97]
	ds_read_b128 v[206:209], v17 offset:256
	ds_read_b128 v[210:213], v17 offset:12544
	ds_read_b128 v[214:217], v185 offset:256
	ds_read_b128 v[218:221], v185 offset:12544
	s_waitcnt lgkmcnt(8)
	v_mfma_f32_32x32x16_bf16 v[98:113], v[4:7], v[138:141], v[98:113]
	v_mfma_f32_32x32x16_bf16 v[98:113], v[12:15], v[142:145], v[98:113]
	v_mfma_f32_32x32x16_bf16 v[82:97], v[8:11], v[138:141], v[82:97]
	v_mfma_f32_32x32x16_bf16 v[82:97], v[186:189], v[142:145], v[82:97]
	s_waitcnt lgkmcnt(4)
	v_mfma_f32_32x32x16_bf16 v[98:113], v[190:193], v[146:149], v[98:113]
	v_mfma_f32_32x32x16_bf16 v[98:113], v[198:201], v[154:157], v[98:113]
	v_mfma_f32_32x32x16_bf16 v[82:97], v[194:197], v[146:149], v[82:97]
	v_mfma_f32_32x32x16_bf16 v[82:97], v[202:205], v[154:157], v[82:97]
	s_waitcnt lgkmcnt(0)
	v_mfma_f32_32x32x16_bf16 v[98:113], v[206:209], v[150:153], v[98:113]
	v_mfma_f32_32x32x16_bf16 v[98:113], v[214:217], v[158:161], v[98:113]
	v_mfma_f32_32x32x16_bf16 v[82:97], v[210:213], v[150:153], v[82:97]
	v_mfma_f32_32x32x16_bf16 v[82:97], v[218:221], v[158:161], v[82:97]
	s_branch .LBB0_1016

; #define LAS __attribute__((address_space(3)))
; __device__ __forceinline__ void attn_issue_k(const Frame& F, const unsigned char* ktile, LAS unsigned char* buf) {
;     unsigned lo = F.lane * 16; asm volatile("" : "+v"(lo));
; #pragma unroll
;     for (int j = 0; j < 3; ++j) __builtin_amdgcn_global_load_lds((const unsigned*)(ktile + (size_t)(F.wave * 3 + j) * 1024 + lo), (LAS unsigned*)(buf + (F.wave * 3 + j) * 1024), 16, 0, 0);
; }
.LBB0_1027:
	s_setprio 1
	s_min_u32 s75, s33, s45
	s_mul_i32 s0, s75, 0x6000
	s_add_u32 s0, s40, s0
	s_addc_u32 s1, s41, 0
	s_mul_i32 s88, s74, 0x6000
	v_mov_b32_e32 v2, v164
	s_add_i32 s88, s88, 0
	s_mov_b32 s98, s0
	s_mov_b32 s99, s1
	s_mov_b32 vcc_lo, s88
	s_cmp_le_u32 s72, s70
	s_cselect_b64 s[0:1], -1, 0
	s_cmp_gt_u32 s72, s70
	s_cbranch_scc1 .Lmy_attn_skipqk_a
	s_mul_i32 s88, s73, 0x6000
	v_add_u32_e32 v2, s88, v174
	v_add_u32_e32 v16, s88, v175
	ds_read_b128 v[4:7], v2
	ds_read_b128 v[8:11], v2 offset:12288
	ds_read_b128 v[12:15], v16
	ds_read_b128 v[180:183], v16 offset:12288
	v_add_u32_e32 v17, s88, v176
	v_add_u32_e32 v179, s88, v177
	ds_read_b128 v[184:187], v17
	ds_read_b128 v[188:191], v17 offset:12288
	ds_read_b128 v[192:195], v179
	ds_read_b128 v[196:199], v179 offset:12288
	s_waitcnt lgkmcnt(5)
	v_mfma_f32_32x32x16_bf16 v[98:113], v[4:7], v[114:117], 0
	v_mfma_f32_32x32x16_bf16 v[98:113], v[12:15], v[118:121], v[98:113]
	ds_read_b128 v[200:203], v2 offset:128
	ds_read_b128 v[204:207], v2 offset:12416
	ds_read_b128 v[208:211], v16 offset:128
	ds_read_b128 v[212:215], v16 offset:12416
	s_waitcnt lgkmcnt(8)
	v_mfma_f32_32x32x16_bf16 v[82:97], v[8:11], v[114:117], 0
	s_add_i32 m0, vcc_lo, s56
	s_add_u32 s100, s98, s8
	s_addc_u32 s101, s99, s9
	global_load_lds_dwordx4 v164, s[100:101]
	v_mfma_f32_32x32x16_bf16 v[82:97], v[180:183], v[118:121], v[82:97]
	s_add_i32 m0, vcc_lo, s57
	s_add_u32 s100, s98, s10
	s_addc_u32 s101, s99, s11
	global_load_lds_dwordx4 v164, s[100:101]
	s_add_i32 m0, vcc_lo, s58
	s_add_u32 s100, s98, s12
	s_addc_u32 s101, s99, s13
	global_load_lds_dwordx4 v164, s[100:101]
	ds_read_b128 v[4:7], v17 offset:128
	ds_read_b128 v[8:11], v17 offset:12416
	ds_read_b128 v[12:15], v179 offset:128
	ds_read_b128 v[180:183], v179 offset:12416
	s_waitcnt lgkmcnt(8)
	v_mfma_f32_32x32x16_bf16 v[98:113], v[184:187], v[122:125], v[98:113]
	v_mfma_f32_32x32x16_bf16 v[98:113], v[192:195], v[126:129], v[98:113]
	v_mfma_f32_32x32x16_bf16 v[82:97], v[188:191], v[122:125], v[82:97]
	v_mfma_f32_32x32x16_bf16 v[82:97], v[196:199], v[126:129], v[82:97]
	ds_read_b128 v[184:187], v2 offset:256
	ds_read_b128 v[188:191], v2 offset:12544
	ds_read_b128 v[192:195], v16 offset:256
	ds_read_b128 v[196:199], v16 offset:12544
	s_waitcnt lgkmcnt(8)
	v_mfma_f32_32x32x16_bf16 v[98:113], v[200:203], v[130:133], v[98:113]
	v_mfma_f32_32x32x16_bf16 v[98:113], v[208:211], v[134:137], v[98:113]
	v_mfma_f32_32x32x16_bf16 v[82:97], v[204:207], v[130:133], v[82:97]
	v_mfma_f32_32x32x16_bf16 v[82:97], v[212:215], v[134:137], v[82:97]
	ds_read_b128 v[200:203], v17 offset:256
	ds_read_b128 v[204:207], v17 offset:12544
	ds_read_b128 v[208:211], v179 offset:256
	ds_read_b128 v[212:215], v179 offset:12544
	s_waitcnt lgkmcnt(8)
	v_mfma_f32_32x32x16_bf16 v[98:113], v[4:7], v[138:141], v[98:113]
	v_mfma_f32_32x32x16_bf16 v[98:113], v[12:15], v[142:145], v[98:113]
	v_mfma_f32_32x32x16_bf16 v[82:97], v[8:11], v[138:141], v[82:97]
	v_mfma_f32_32x32x16_bf16 v[82:97], v[180:183], v[142:145], v[82:97]
	s_waitcnt lgkmcnt(4)
	v_mfma_f32_32x32x16_bf16 v[98:113], v[184:187], v[146:149], v[98:113]
	v_mfma_f32_32x32x16_bf16 v[98:113], v[192:195], v[154:157], v[98:113]
	v_mfma_f32_32x32x16_bf16 v[82:97], v[188:191], v[146:149], v[82:97]
	v_mfma_f32_32x32x16_bf16 v[82:97], v[196:199], v[154:157], v[82:97]
	s_waitcnt lgkmcnt(0)
	v_mfma_f32_32x32x16_bf16 v[98:113], v[200:203], v[150:153], v[98:113]
	v_mfma_f32_32x32x16_bf16 v[98:113], v[208:211], v[158:161], v[98:113]
	v_mfma_f32_32x32x16_bf16 v[82:97], v[204:207], v[150:153], v[82:97]
	v_mfma_f32_32x32x16_bf16 v[82:97], v[212:215], v[158:161], v[82:97]
	s_branch .LBB0_1030
